# ffn_conv: waves 4-7 run at s_setprio 1 while waves 0-3 keep the priority 2 left by the up GEMM (asymmetric arbitration between the two waves of a SIMD), on top of v062
# speedup vs baseline: 1.0035x; 1.0000x over previous
; __device__ __forceinline__ int fresh_lane() { int l; asm volatile("v_mbcnt_lo_u32_b32 %0, -1, 0\n\tv_mbcnt_hi_u32_b32 %0, -1, %0" : "=v"(l)); return l; }
; __device__ __forceinline__ void fresh_ids(Frame& F) { F.lane = fresh_lane(); F.tid = F.wave * 64 + F.lane; }
; __device__ __forceinline__ void ffn_conv_phase(Frame& F, int L, int nrows, bool probe_alt = false) {
;     fresh_ids(F);
;     const int gw = blockIdx.x * NWAVES + F.wave, NGW = F.G * NWAVES;
;     const bf16_t* gate = (const bf16_t*)(F.ws + WS_GATE); bf16_t* val = (bf16_t*)(F.ws + WS_VAL);
;     const float* cw = F.in[I_FCW] + (size_t)L * 9 * DFF; const float* cb_ = F.in[I_FCB] + (size_t)L * DFF;
;     const int NTB = nrows / 64; constexpr int NCB = DFF / 64;
;     for (int job = gw; job < NTB * NCB; job += NGW) {
;         const int lane = fresh_lane(), cq = lane & 7, tq = lane >> 3;
;         const int cb = job / NTB, tb = job % NTB;
;         const int rb = tb * 64, c0 = cb * 64 + cq * 8;
;         const bool lat = rb < MLAT;
;         const int gr = lat ? (tb & 31) : 0, base = lat ? (rb - gr * 64) : (MLAT + (((rb - MLAT) >> 8) << 8)), q = lat ? 0 : (((rb - MLAT) >> 6) & 3);
;         u32x4 raw[3][10], rv[8];
.LBB0_1202:
	s_andn2_b64 vcc, exec, s[0:1]
	s_cbranch_vccnz .LBB0_1319
	s_cmp_lt_u32 s33, 0x100
	s_cbranch_scc1 .Lffn_prio_skip
	s_setprio 1
.Lffn_prio_skip:
	v_readlane_b32 s0, v255, 35
	s_lshr_b32 s6, s0, 6
	s_mul_i32 s7, s6, 0x58
	v_readlane_b32 s0, v255, 4
	s_cmp_ge_i32 s0, s7
	v_readlane_b32 s1, v255, 5
	s_waitcnt vmcnt(0)
	v_mbcnt_lo_u32_b32 v0, -1, 0
	v_mbcnt_hi_u32_b32 v0, -1, v0
	s_cbranch_scc1 .LBB0_1266
	s_mul_i32 s0, s82, 0x31800
	s_mul_hi_u32 s1, s82, 0x31800
	s_add_u32 s0, s56, s0
	s_addc_u32 s1, s57, s1
	s_mul_i32 s5, s82, 0x5800
	s_mul_hi_u32 s4, s82, 0x5800
	s_add_u32 s10, s58, s5
	s_addc_u32 s11, s59, s4
	s_add_u32 s30, s0, 0x10800
	s_addc_u32 s31, s1, 0
	s_add_u32 s34, s0, 0x16000
	s_addc_u32 s35, s1, 0
	s_add_u32 s44, s0, 0x1b800
	s_addc_u32 s45, s1, 0
	s_add_u32 s46, s0, 0x21000
	s_addc_u32 s47, s1, 0
	s_add_u32 s48, s0, 0x26800
	s_addc_u32 s49, s1, 0
	s_add_u32 s50, s0, 0x2c000
	s_addc_u32 s51, s1, 0
	s_abs_i32 s14, s6
	v_cvt_f32_u32_e32 v0, s14
	v_readlane_b32 s36, v255, 4
	s_lshl_b32 s4, s36, 6
	s_sub_i32 s5, 0, s14
	v_rcp_iflag_f32_e32 v0, v0
	s_or_b32 s72, s4, 7
	s_lshl_b32 s26, s6, 6
	s_ashr_i32 s15, s6, 31
	v_mul_f32_e32 v0, 0x4f7ffffe, v0
	v_cvt_u32_f32_e32 v0, v0
	s_sub_i32 s75, 0, s26
	s_sub_i32 s76, 0, s6
	s_mov_b32 s77, s36
	v_readfirstlane_b32 s4, v0
	s_mul_i32 s5, s5, s4
	s_mul_hi_u32 s5, s4, s5
	s_add_i32 s73, s4, s5
	v_readlane_b32 s4, v255, 28
	s_lshl_b32 s74, s4, 6
	v_readlane_b32 s37, v255, 5
	v_readlane_b32 s5, v255, 29
	s_branch .LBB0_1206
